# v66 plus 7 of 16 stash pieces kept in free LDS instead of global scratch
# baseline (speedup 1.0000x reference)
; __device__ __forceinline__ float hsum(float v) { auto rr = __builtin_amdgcn_permlane32_swap(__float_as_uint(v), __float_as_uint(v), false, false); return __uint_as_float(rr[0]) + __uint_as_float(rr[1]); }
; __device__ __forceinline__ void da_unit(LAS unsigned char* lds, const AttnP& P, int seqbase, int S, int h, int qb, float lam) {
;     ...
;         int tid3 = threadIdx.x; asm volatile("" : "+v"(tid3));
;         f32x4* stash = (f32x4*)(P.stash + (size_t)blockIdx.x * 32768 + tid3 * 64);
;         if (map == 0) {
;             const float inv = 1.0f / hsum(l);
; #pragma unroll
;             for (int db = 0; db < 4; ++db)
; #pragma unroll
;                 for (int g = 0; g < 4; ++g) stash[db * 4 + g] = (f32x4){o[db][4 * g], o[db][4 * g + 1], o[db][4 * g + 2], o[db][4 * g + 3]} * inv;
;         } else {
;             const float inv = lam / hsum(l);
; #pragma unroll
;             for (int db = 0; db < 4; ++db)
; #pragma unroll
;                 for (int g = 0; g < 4; ++g) {
;                     const f32x4 st = stash[db * 4 + g];
; #pragma unroll
;                     for (int e = 0; e < 4; ++e) { const float a = st[e] - o[db][4 * g + e] * inv; o[db][4 * g + e] = a; ss += a * a; }
.LBB0_450:
	v_mov_b32_e32 v2, v151
	s_and_b64 vcc, exec, s[58:59]
	v_lshrrev_b32_e32 v3, 6, v2
	v_and_b32_e32 v2, 63, v2
	v_lshlrev_b32_e32 v3, 14, v3
	v_lshl_or_b32 v246, v2, 4, v3
	v_add_u32_e32 v247, 0x1000, v246
	v_add_u32_e32 v248, 0x2000, v246
	v_add_u32_e32 v249, 0x3000, v246
	v_lshlrev_b32_e32 v3, 4, v151
	v_add_u32_e32 v2, 0x18000, v3
	v_add_u32_e32 v3, 0x1c700, v3
	s_cbranch_vccz .LBB0_452
	ds_read_b128 v[4:7], v2 offset:0
	ds_read_b128 v[8:11], v2 offset:8192
	ds_read_b128 v[12:15], v3 offset:0
	ds_read_b128 v[80:83], v3 offset:8192
	ds_read_b128 v[84:87], v3 offset:16384
	ds_read_b128 v[88:91], v3 offset:24576
	ds_read_b128 v[92:95], v3 offset:32768
	global_load_dwordx4 v[98:101], v247, s[20:21] offset:3072
	global_load_dwordx4 v[102:105], v248, s[20:21] offset:0
	global_load_dwordx4 v[132:135], v248, s[20:21] offset:1024
	global_load_dwordx4 v[136:139], v248, s[20:21] offset:2048
	global_load_dwordx4 v[140:143], v248, s[20:21] offset:3072
	global_load_dwordx4 v[144:147], v249, s[20:21] offset:3072
	global_load_dwordx4 v[160:163], v249, s[20:21] offset:2048
	global_load_dwordx4 v[164:167], v249, s[20:21] offset:1024
	global_load_dwordx4 v[168:171], v249, s[20:21] offset:0
	v_mov_b32_e32 v96, v0
	v_mov_b32_e32 v97, v0
	s_nop 1
	v_permlane32_swap_b32_e32 v96, v97
	v_add_f32_e32 v96, v96, v97
	v_div_scale_f32 v97, s[10:11], v96, v96, v211
	v_rcp_f32_e32 v106, v97
	v_div_scale_f32 v107, vcc, v211, v96, v211
	v_fma_f32 v108, -v97, v106, 1.0
	v_fmac_f32_e32 v106, v108, v106
	v_mul_f32_e32 v108, v107, v106
	v_fma_f32 v109, -v97, v108, v107
	v_fmac_f32_e32 v108, v109, v106
	v_fma_f32 v97, -v97, v108, v107
	v_div_fmas_f32 v97, v97, v106, v108
	v_div_fixup_f32 v172, v97, v96, v211
	s_waitcnt vmcnt(0) lgkmcnt(0)
	v_pk_fma_f32 v[130:131], v[64:65], v[172:173], v[4:5] op_sel_hi:[1,0,1] neg_lo:[1,0,0] neg_hi:[1,0,0]
	v_pk_fma_f32 v[128:129], v[66:67], v[172:173], v[6:7] op_sel_hi:[1,0,1] neg_lo:[1,0,0] neg_hi:[1,0,0]
	s_waitcnt vmcnt(14)
	v_pk_fma_f32 v[126:127], v[68:69], v[172:173], v[8:9] op_sel_hi:[1,0,1] neg_lo:[1,0,0] neg_hi:[1,0,0]
	s_waitcnt vmcnt(12)
	v_pk_fma_f32 v[116:117], v[76:77], v[172:173], v[80:81] op_sel_hi:[1,0,1] neg_lo:[1,0,0] neg_hi:[1,0,0]
	v_pk_mul_f32 v[80:81], v[130:131], v[130:131]
	v_pk_fma_f32 v[114:115], v[78:79], v[172:173], v[82:83] op_sel_hi:[1,0,1] neg_lo:[1,0,0] neg_hi:[1,0,0]
	v_add_f32_e32 v80, v222, v80
	v_pk_mul_f32 v[82:83], v[128:129], v[128:129]
	v_add_f32_e32 v80, v81, v80
	v_add_f32_e32 v80, v82, v80
	s_waitcnt vmcnt(11)
	v_pk_fma_f32 v[118:119], v[48:49], v[172:173], v[84:85] op_sel_hi:[1,0,1] neg_lo:[1,0,0] neg_hi:[1,0,0]
	v_pk_mul_f32 v[84:85], v[126:127], v[126:127]
	v_add_f32_e32 v80, v83, v80
	v_pk_fma_f32 v[124:125], v[70:71], v[172:173], v[10:11] op_sel_hi:[1,0,1] neg_lo:[1,0,0] neg_hi:[1,0,0]
	v_add_f32_e32 v80, v84, v80
	s_waitcnt vmcnt(10)
	v_pk_fma_f32 v[110:111], v[52:53], v[172:173], v[88:89] op_sel_hi:[1,0,1] neg_lo:[1,0,0] neg_hi:[1,0,0]
	v_pk_mul_f32 v[88:89], v[124:125], v[124:125]
	v_add_f32_e32 v80, v85, v80
	v_pk_fma_f32 v[122:123], v[72:73], v[172:173], v[12:13] op_sel_hi:[1,0,1] neg_lo:[1,0,0] neg_hi:[1,0,0]
	v_add_f32_e32 v80, v88, v80
	s_waitcnt vmcnt(9)
	v_pk_fma_f32 v[106:107], v[56:57], v[172:173], v[92:93] op_sel_hi:[1,0,1] neg_lo:[1,0,0] neg_hi:[1,0,0]
	s_waitcnt vmcnt(8)
	v_pk_fma_f32 v[92:93], v[60:61], v[172:173], v[98:99] op_sel_hi:[1,0,1] neg_lo:[1,0,0] neg_hi:[1,0,0]
	v_pk_mul_f32 v[98:99], v[122:123], v[122:123]
	v_add_f32_e32 v80, v89, v80
	v_pk_fma_f32 v[120:121], v[74:75], v[172:173], v[14:15] op_sel_hi:[1,0,1] neg_lo:[1,0,0] neg_hi:[1,0,0]
	v_add_f32_e32 v80, v98, v80
	v_pk_fma_f32 v[108:109], v[54:55], v[172:173], v[90:91] op_sel_hi:[1,0,1] neg_lo:[1,0,0] neg_hi:[1,0,0]
	v_pk_fma_f32 v[90:91], v[62:63], v[172:173], v[100:101] op_sel_hi:[1,0,1] neg_lo:[1,0,0] neg_hi:[1,0,0]
	v_pk_mul_f32 v[100:101], v[120:121], v[120:121]
	v_add_f32_e32 v80, v99, v80
	v_add_f32_e32 v80, v100, v80
	v_pk_fma_f32 v[96:97], v[58:59], v[172:173], v[94:95] op_sel_hi:[1,0,1] neg_lo:[1,0,0] neg_hi:[1,0,0]
	s_waitcnt vmcnt(7)
	v_pk_fma_f32 v[94:95], v[32:33], v[172:173], v[102:103] op_sel_hi:[1,0,1] neg_lo:[1,0,0] neg_hi:[1,0,0]
	v_pk_mul_f32 v[102:103], v[116:117], v[116:117]
	v_add_f32_e32 v80, v101, v80
	v_add_f32_e32 v80, v102, v80
	v_pk_fma_f32 v[112:113], v[50:51], v[172:173], v[86:87] op_sel_hi:[1,0,1] neg_lo:[1,0,0] neg_hi:[1,0,0]
	v_pk_fma_f32 v[86:87], v[34:35], v[172:173], v[104:105] op_sel_hi:[1,0,1] neg_lo:[1,0,0] neg_hi:[1,0,0]
	v_pk_mul_f32 v[104:105], v[114:115], v[114:115]
	v_add_f32_e32 v80, v103, v80
	v_add_f32_e32 v80, v104, v80
	s_waitcnt vmcnt(6)
; __device__ __forceinline__ void da_unit(LAS unsigned char* lds, const AttnP& P, int seqbase, int S, int h, int qb, float lam) {
;     ...
;                 for (int g = 0; g < 4; ++g) {
;                     const f32x4 st = stash[db * 4 + g];
; #pragma unroll
;                     for (int e = 0; e < 4; ++e) { const float a = st[e] - o[db][4 * g + e] * inv; o[db][4 * g + e] = a; ss += a * a; }
	v_pk_fma_f32 v[14:15], v[36:37], v[172:173], v[132:133] op_sel_hi:[1,0,1] neg_lo:[1,0,0] neg_hi:[1,0,0]
	v_pk_mul_f32 v[132:133], v[118:119], v[118:119]
	v_add_f32_e32 v80, v105, v80
	v_add_f32_e32 v80, v132, v80
	v_pk_fma_f32 v[12:13], v[38:39], v[172:173], v[134:135] op_sel_hi:[1,0,1] neg_lo:[1,0,0] neg_hi:[1,0,0]
	v_pk_mul_f32 v[134:135], v[112:113], v[112:113]
	v_add_f32_e32 v80, v133, v80
	v_add_f32_e32 v80, v134, v80
	s_waitcnt vmcnt(5)
	v_pk_fma_f32 v[10:11], v[40:41], v[172:173], v[136:137] op_sel_hi:[1,0,1] neg_lo:[1,0,0] neg_hi:[1,0,0]
	v_pk_mul_f32 v[136:137], v[110:111], v[110:111]
	v_add_f32_e32 v80, v135, v80
	v_add_f32_e32 v80, v136, v80
	v_pk_fma_f32 v[8:9], v[42:43], v[172:173], v[138:139] op_sel_hi:[1,0,1] neg_lo:[1,0,0] neg_hi:[1,0,0]
	v_pk_mul_f32 v[138:139], v[108:109], v[108:109]
	v_add_f32_e32 v80, v137, v80
	v_add_f32_e32 v80, v138, v80
	s_waitcnt vmcnt(4)
	v_pk_fma_f32 v[6:7], v[44:45], v[172:173], v[140:141] op_sel_hi:[1,0,1] neg_lo:[1,0,0] neg_hi:[1,0,0]
	v_pk_mul_f32 v[140:141], v[106:107], v[106:107]
	v_add_f32_e32 v80, v139, v80
	v_add_f32_e32 v80, v140, v80
	v_pk_fma_f32 v[4:5], v[46:47], v[172:173], v[142:143] op_sel_hi:[1,0,1] neg_lo:[1,0,0] neg_hi:[1,0,0]
	v_pk_mul_f32 v[142:143], v[96:97], v[96:97]
	v_add_f32_e32 v80, v141, v80
	v_add_f32_e32 v80, v142, v80
	v_pk_mul_f32 v[174:175], v[92:93], v[92:93]
	v_add_f32_e32 v80, v143, v80
	v_add_f32_e32 v80, v174, v80
	v_pk_mul_f32 v[176:177], v[90:91], v[90:91]
	v_add_f32_e32 v80, v175, v80
	v_add_f32_e32 v80, v176, v80
	v_pk_mul_f32 v[178:179], v[94:95], v[94:95]
	v_add_f32_e32 v80, v177, v80
	v_add_f32_e32 v80, v178, v80
	v_pk_mul_f32 v[180:181], v[86:87], v[86:87]
	v_add_f32_e32 v80, v179, v80
	v_add_f32_e32 v80, v180, v80
	v_pk_mul_f32 v[182:183], v[14:15], v[14:15]
	v_add_f32_e32 v80, v181, v80
	v_add_f32_e32 v80, v182, v80
	v_pk_mul_f32 v[184:185], v[12:13], v[12:13]
	v_add_f32_e32 v80, v183, v80
	v_add_f32_e32 v80, v184, v80
	v_pk_mul_f32 v[186:187], v[10:11], v[10:11]
	v_add_f32_e32 v80, v185, v80
	v_add_f32_e32 v80, v186, v80
	v_pk_mul_f32 v[188:189], v[8:9], v[8:9]
	v_add_f32_e32 v80, v187, v80
	v_add_f32_e32 v80, v188, v80
	v_pk_mul_f32 v[190:191], v[6:7], v[6:7]
	v_add_f32_e32 v80, v189, v80
	v_add_f32_e32 v80, v190, v80
	v_add_f32_e32 v82, v191, v80
	v_pk_mul_f32 v[80:81], v[4:5], v[4:5]
	s_waitcnt vmcnt(0)
	v_pk_fma_f32 v[102:103], v[16:17], v[172:173], v[168:169] op_sel_hi:[1,0,1] neg_lo:[1,0,0] neg_hi:[1,0,0]
	v_add_f32_e32 v80, v80, v82
	v_add_f32_e32 v82, v81, v80
	v_pk_mul_f32 v[80:81], v[102:103], v[102:103]
	v_pk_fma_f32 v[104:105], v[18:19], v[172:173], v[170:171] op_sel_hi:[1,0,1] neg_lo:[1,0,0] neg_hi:[1,0,0]
	v_add_f32_e32 v80, v80, v82
	v_add_f32_e32 v82, v81, v80
	v_pk_mul_f32 v[80:81], v[104:105], v[104:105]
	v_pk_fma_f32 v[98:99], v[20:21], v[172:173], v[164:165] op_sel_hi:[1,0,1] neg_lo:[1,0,0] neg_hi:[1,0,0]
	v_add_f32_e32 v80, v80, v82
	v_add_f32_e32 v82, v81, v80
	v_pk_mul_f32 v[80:81], v[98:99], v[98:99]
	v_pk_fma_f32 v[100:101], v[22:23], v[172:173], v[166:167] op_sel_hi:[1,0,1] neg_lo:[1,0,0] neg_hi:[1,0,0]
	v_add_f32_e32 v80, v80, v82
	v_add_f32_e32 v82, v81, v80
	v_pk_mul_f32 v[80:81], v[100:101], v[100:101]
	v_pk_fma_f32 v[88:89], v[24:25], v[172:173], v[160:161] op_sel_hi:[1,0,1] neg_lo:[1,0,0] neg_hi:[1,0,0]
	v_add_f32_e32 v80, v80, v82
	v_add_f32_e32 v82, v81, v80
	v_pk_mul_f32 v[80:81], v[88:89], v[88:89]
	v_pk_fma_f32 v[84:85], v[26:27], v[172:173], v[162:163] op_sel_hi:[1,0,1] neg_lo:[1,0,0] neg_hi:[1,0,0]
	v_add_f32_e32 v80, v80, v82
	v_add_f32_e32 v82, v81, v80
	v_pk_mul_f32 v[80:81], v[84:85], v[84:85]
	s_nop 0
	v_add_f32_e32 v80, v80, v82
	v_add_f32_e32 v132, v81, v80
	v_pk_fma_f32 v[80:81], v[28:29], v[172:173], v[144:145] op_sel_hi:[1,0,1] neg_lo:[1,0,0] neg_hi:[1,0,0]
	s_nop 0
	v_pk_mul_f32 v[82:83], v[80:81], v[80:81]
	s_nop 0
	v_add_f32_e32 v82, v82, v132
	v_add_f32_e32 v134, v83, v82
	v_pk_fma_f32 v[82:83], v[30:31], v[172:173], v[146:147] op_sel_hi:[1,0,1] neg_lo:[1,0,0] neg_hi:[1,0,0]
	s_nop 0
	v_pk_mul_f32 v[132:133], v[82:83], v[82:83]
	s_nop 0
	v_add_f32_e32 v132, v132, v134
	v_add_f32_e32 v132, v133, v132
	s_cbranch_execz .LBB0_453
	s_branch .LBB0_454

; __device__ __forceinline__ float hsum(float v) { auto rr = __builtin_amdgcn_permlane32_swap(__float_as_uint(v), __float_as_uint(v), false, false); return __uint_as_float(rr[0]) + __uint_as_float(rr[1]); }
; __device__ __forceinline__ void da_unit(LAS unsigned char* lds, const AttnP& P, int seqbase, int S, int h, int qb, float lam) {
;     ...
;         if (map == 0) {
;             const float inv = 1.0f / hsum(l);
; #pragma unroll
;             for (int db = 0; db < 4; ++db)
; #pragma unroll
;                 for (int g = 0; g < 4; ++g) stash[db * 4 + g] = (f32x4){o[db][4 * g], o[db][4 * g + 1], o[db][4 * g + 2], o[db][4 * g + 3]} * inv;
.LBB0_453:
	v_mov_b32_e32 v132, v0
	s_nop 1
	v_permlane32_swap_b32_e32 v0, v132
	v_add_f32_e32 v0, v0, v132
	v_div_scale_f32 v132, s[10:11], v0, v0, 1.0
	v_rcp_f32_e32 v133, v132
	s_nop 0
	v_fma_f32 v134, -v132, v133, 1.0
	v_fmac_f32_e32 v133, v134, v133
	v_div_scale_f32 v134, vcc, 1.0, v0, 1.0
	v_mul_f32_e32 v135, v134, v133
	v_fma_f32 v136, -v132, v135, v134
	v_fmac_f32_e32 v135, v136, v133
	v_fma_f32 v132, -v132, v135, v134
	v_div_fmas_f32 v132, v132, v133, v135
	v_div_fixup_f32 v0, v132, v0, 1.0
	v_pk_mul_f32 v[66:67], v[66:67], v[0:1] op_sel_hi:[1,0]
	v_pk_mul_f32 v[64:65], v[64:65], v[0:1] op_sel_hi:[1,0]
	v_pk_mul_f32 v[50:51], v[50:51], v[0:1] op_sel_hi:[1,0]
	v_pk_mul_f32 v[48:49], v[48:49], v[0:1] op_sel_hi:[1,0]
	v_pk_mul_f32 v[34:35], v[34:35], v[0:1] op_sel_hi:[1,0]
	v_pk_mul_f32 v[32:33], v[32:33], v[0:1] op_sel_hi:[1,0]
	v_pk_mul_f32 v[18:19], v[18:19], v[0:1] op_sel_hi:[1,0]
	v_pk_mul_f32 v[16:17], v[16:17], v[0:1] op_sel_hi:[1,0]
	ds_write_b128 v2, v[64:67] offset:0
	ds_write_b128 v3, v[48:51] offset:16384
	global_store_dwordx4 v248, v[32:35], s[20:21] offset:0
	v_pk_mul_f32 v[66:67], v[70:71], v[0:1] op_sel_hi:[1,0]
	v_pk_mul_f32 v[64:65], v[68:69], v[0:1] op_sel_hi:[1,0]
	v_pk_mul_f32 v[50:51], v[54:55], v[0:1] op_sel_hi:[1,0]
	v_pk_mul_f32 v[48:49], v[52:53], v[0:1] op_sel_hi:[1,0]
	v_pk_mul_f32 v[34:35], v[38:39], v[0:1] op_sel_hi:[1,0]
	v_pk_mul_f32 v[32:33], v[36:37], v[0:1] op_sel_hi:[1,0]
	global_store_dwordx4 v249, v[16:19], s[20:21] offset:0
	ds_write_b128 v2, v[64:67] offset:8192
	ds_write_b128 v3, v[48:51] offset:24576
	v_pk_mul_f32 v[18:19], v[22:23], v[0:1] op_sel_hi:[1,0]
	v_pk_mul_f32 v[16:17], v[20:21], v[0:1] op_sel_hi:[1,0]
	v_pk_mul_f32 v[66:67], v[74:75], v[0:1] op_sel_hi:[1,0]
	v_pk_mul_f32 v[64:65], v[72:73], v[0:1] op_sel_hi:[1,0]
	v_pk_mul_f32 v[50:51], v[58:59], v[0:1] op_sel_hi:[1,0]
	v_pk_mul_f32 v[48:49], v[56:57], v[0:1] op_sel_hi:[1,0]
	global_store_dwordx4 v248, v[32:35], s[20:21] offset:1024
	global_store_dwordx4 v249, v[16:19], s[20:21] offset:1024
	ds_write_b128 v3, v[64:67] offset:0
	v_pk_mul_f32 v[34:35], v[42:43], v[0:1] op_sel_hi:[1,0]
	v_pk_mul_f32 v[32:33], v[40:41], v[0:1] op_sel_hi:[1,0]
	v_pk_mul_f32 v[18:19], v[26:27], v[0:1] op_sel_hi:[1,0]
	v_pk_mul_f32 v[16:17], v[24:25], v[0:1] op_sel_hi:[1,0]
	v_pk_mul_f32 v[66:67], v[78:79], v[0:1] op_sel_hi:[1,0]
	v_pk_mul_f32 v[64:65], v[76:77], v[0:1] op_sel_hi:[1,0]
	ds_write_b128 v3, v[48:51] offset:32768
	global_store_dwordx4 v248, v[32:35], s[20:21] offset:2048
	global_store_dwordx4 v249, v[16:19], s[20:21] offset:2048
	v_pk_mul_f32 v[50:51], v[62:63], v[0:1] op_sel_hi:[1,0]
	v_pk_mul_f32 v[48:49], v[60:61], v[0:1] op_sel_hi:[1,0]
	v_pk_mul_f32 v[34:35], v[46:47], v[0:1] op_sel_hi:[1,0]
	v_pk_mul_f32 v[32:33], v[44:45], v[0:1] op_sel_hi:[1,0]
	v_pk_mul_f32 v[18:19], v[30:31], v[0:1] op_sel_hi:[1,0]
	v_pk_mul_f32 v[16:17], v[28:29], v[0:1] op_sel_hi:[1,0]
	v_mov_b32_e32 v132, v222
	ds_write_b128 v3, v[64:67] offset:8192
	global_store_dwordx4 v247, v[48:51], s[20:21] offset:3072
	global_store_dwordx4 v248, v[32:35], s[20:21] offset:3072
	global_store_dwordx4 v249, v[16:19], s[20:21] offset:3072
